# attention q-block prologue: q-norm gain vector pairs P2..P7 (12 loads) issued together after pair P1 into dead registers instead of 6 serialized load-wait-use round trips
# baseline (speedup 1.0000x reference)
.LBB0_1051:
	s_and_b64 s[0:1], s[68:69], exec
	v_readlane_b32 s0, v254, 48
	s_cselect_b32 s76, s87, s0
	s_or_b32 s96, s92, s76
	s_mul_hi_u32 s1, s96, 0x1800
	s_mul_i32 s4, s93, 0x1800
	s_mul_i32 s0, s96, 0x1800
	s_add_i32 s1, s1, s4
	v_readlane_b32 s4, v254, 49
	v_mov_b32_e32 v195, v184
	s_add_u32 s0, s4, s0
	v_readlane_b32 s4, v254, 50
	s_addc_u32 s1, s4, s1
	v_readfirstlane_b32 s77, v195
	s_ashr_i32 s73, s77, 6
	v_and_b32_e32 v194, 31, v195
	s_lshl_b32 s88, s73, 5
	v_bfe_u32 v193, v195, 5, 1
	v_or_b32_e32 v98, s88, v194
	v_mov_b64_e32 v[2:3], s[0:1]
	v_mad_i64_i32 v[2:3], s[0:1], v98, s75, v[2:3]
	v_lshlrev_b32_e32 v58, 4, v193
	v_mov_b32_e32 v59, v1
	v_lshl_add_u64 v[62:63], v[2:3], 0, v[58:59]
	global_load_dwordx4 v[22:25], v[62:63], off
	global_load_dwordx4 v[26:29], v[62:63], off offset:32
	global_load_dwordx4 v[30:33], v[62:63], off offset:64
	global_load_dwordx4 v[36:39], v[62:63], off offset:96
	v_ashrrev_i32_e32 v96, 3, v195
	v_lshlrev_b32_e32 v59, 4, v195
	v_mov_b32_e32 v53, v1
	v_mad_i64_i32 v[2:3], s[0:1], v96, s75, v[166:167]
	v_and_b32_e32 v52, 0x70, v59
	v_lshl_add_u64 v[2:3], v[2:3], 0, v[52:53]
	global_load_dwordx4 v[2:5], v[2:3], off offset:256
	v_ashrrev_i32_e32 v56, 4, v195
	global_load_dwordx4 v[40:43], v[62:63], off offset:128
	v_lshlrev_b32_e32 v138, 3, v195
	v_add_u32_e32 v76, 32, v56
	v_and_b32_e32 v0, 0x78, v138
	v_ashrrev_i32_e32 v57, 31, v56
	v_ashrrev_i32_e32 v77, 31, v76
	v_lshlrev_b32_e32 v0, 1, v0
	v_lshlrev_b64 v[54:55], 12, v[56:57]
	v_mad_i64_i32 v[8:9], s[0:1], v76, s75, v[166:167]
	v_lshlrev_b64 v[12:13], 12, v[76:77]
	v_mad_i64_i32 v[6:7], s[0:1], v56, s75, v[166:167]
	v_lshl_add_u64 v[10:11], s[80:81], 0, v[54:55]
	v_lshl_add_u64 v[78:79], v[8:9], 0, v[0:1]
	v_lshl_add_u64 v[8:9], s[80:81], 0, v[12:13]
	v_lshl_add_u64 v[60:61], v[6:7], 0, v[0:1]
	v_lshl_add_u64 v[6:7], v[10:11], 0, v[0:1]
	v_lshl_add_u64 v[8:9], v[8:9], 0, v[0:1]
	global_load_dwordx4 v[10:13], v[6:7], off
	s_nop 0
	global_load_dwordx4 v[6:9], v[8:9], off
	s_nop 0
	global_load_dwordx4 v[44:47], v[62:63], off offset:160
	global_load_dwordx4 v[48:51], v[62:63], off offset:192
	global_load_dwordx4 v[66:69], v[62:63], off offset:224
	global_load_dwordx4 v[14:17], v[62:63], off offset:288
	global_load_dwordx4 v[18:21], v[62:63], off offset:352
	v_and_b32_e32 v130, 32, v195
	s_mov_b32 s1, 0xf800000
	s_or_b32 s0, s76, s72
	v_readlane_b32 s4, v254, 7
	v_readlane_b32 s6, v254, 9
	v_readlane_b32 s7, v254, 10
	v_readlane_b32 s8, v254, 11
	v_readlane_b32 s9, v254, 12
	v_readlane_b32 s10, v254, 13
	v_readlane_b32 s11, v254, 14
	v_readlane_b32 s12, v254, 15
	v_readlane_b32 s13, v254, 16
	v_readlane_b32 s5, v254, 8
	v_readlane_b32 s14, v254, 17
	v_readlane_b32 s15, v254, 18
	v_readlane_b32 s16, v254, 19
	v_readlane_b32 s17, v254, 20
	v_readlane_b32 s18, v254, 21
	v_readlane_b32 s19, v254, 22
	s_add_i32 s78, s88, s76
	s_waitcnt vmcnt(12)
	v_and_b32_e32 v158, 0xffff0000, v22
	v_lshlrev_b32_e32 v159, 16, v22
	s_waitcnt vmcnt(10)
	v_lshlrev_b32_e32 v150, 16, v30
	v_and_b32_e32 v149, 0xffff0000, v30
	v_lshlrev_b32_e32 v148, 16, v31
	v_and_b32_e32 v147, 0xffff0000, v31
	v_lshlrev_b32_e32 v109, 16, v32
	v_and_b32_e32 v108, 0xffff0000, v32
	v_lshlrev_b32_e32 v107, 16, v33
	v_and_b32_e32 v106, 0xffff0000, v33
	s_waitcnt vmcnt(9)
	v_lshlrev_b32_e32 v145, 16, v36
	v_and_b32_e32 v143, 0xffff0000, v36
	v_lshlrev_b32_e32 v112, 16, v37
	v_and_b32_e32 v111, 0xffff0000, v37
	global_load_dwordx4 v[34:37], v[62:63], off offset:320
	global_load_dwordx4 v[30:33], v[62:63], off offset:256
	v_mul_f32_e32 v64, v158, v158
	v_lshlrev_b32_e32 v157, 16, v23
	v_fmac_f32_e32 v64, v159, v159
	v_and_b32_e32 v99, 0xffff0000, v23
	v_fmac_f32_e32 v64, v157, v157
	v_lshlrev_b32_e32 v156, 16, v24
	v_fmac_f32_e32 v64, v99, v99
	v_and_b32_e32 v100, 0xffff0000, v24
	v_fmac_f32_e32 v64, v156, v156
	v_lshlrev_b32_e32 v155, 16, v25
	v_fmac_f32_e32 v64, v100, v100
	v_and_b32_e32 v101, 0xffff0000, v25
	v_fmac_f32_e32 v64, v155, v155
	v_lshlrev_b32_e32 v154, 16, v26
	v_fmac_f32_e32 v64, v101, v101
	v_and_b32_e32 v102, 0xffff0000, v26
	v_fmac_f32_e32 v64, v154, v154
	v_lshlrev_b32_e32 v153, 16, v27
	v_fmac_f32_e32 v64, v102, v102
	v_and_b32_e32 v103, 0xffff0000, v27
	v_fmac_f32_e32 v64, v153, v153
	v_lshlrev_b32_e32 v152, 16, v28
	v_fmac_f32_e32 v64, v103, v103
	v_and_b32_e32 v104, 0xffff0000, v28
	v_fmac_f32_e32 v64, v152, v152
	v_lshlrev_b32_e32 v151, 16, v29
	v_fmac_f32_e32 v64, v104, v104
	v_and_b32_e32 v105, 0xffff0000, v29
	v_fmac_f32_e32 v64, v151, v151
	v_fmac_f32_e32 v64, v105, v105
	v_fmac_f32_e32 v64, v150, v150
	v_fmac_f32_e32 v64, v149, v149
	v_fmac_f32_e32 v64, v148, v148
	v_fmac_f32_e32 v64, v147, v147
	v_fmac_f32_e32 v64, v109, v109
	v_fmac_f32_e32 v64, v108, v108
	v_fmac_f32_e32 v64, v107, v107
	v_fmac_f32_e32 v64, v106, v106
	v_fmac_f32_e32 v64, v145, v145
	v_fmac_f32_e32 v64, v143, v143
	v_fmac_f32_e32 v64, v112, v112
	v_lshlrev_b32_e32 v110, 16, v38
	v_fmac_f32_e32 v64, v111, v111
	v_fmac_f32_e32 v64, v110, v110
	v_and_b32_e32 v146, 0xffff0000, v38
	v_fmac_f32_e32 v64, v146, v146
	v_lshlrev_b32_e32 v144, 16, v39
	v_fmac_f32_e32 v64, v144, v144
	v_and_b32_e32 v113, 0xffff0000, v39
	v_fmac_f32_e32 v64, v113, v113
	s_waitcnt vmcnt(9)
	v_lshlrev_b32_e32 v142, 16, v40
	v_fmac_f32_e32 v64, v142, v142
	v_and_b32_e32 v141, 0xffff0000, v40
	v_fmac_f32_e32 v64, v141, v141
	v_lshlrev_b32_e32 v140, 16, v41
	v_fmac_f32_e32 v64, v140, v140
	v_and_b32_e32 v139, 0xffff0000, v41
	v_fmac_f32_e32 v64, v139, v139
	v_lshlrev_b32_e32 v117, 16, v42
	v_fmac_f32_e32 v64, v117, v117
	v_and_b32_e32 v116, 0xffff0000, v42
	v_fmac_f32_e32 v64, v116, v116
	v_lshlrev_b32_e32 v115, 16, v43
	v_fmac_f32_e32 v64, v115, v115
	v_and_b32_e32 v114, 0xffff0000, v43
	v_fmac_f32_e32 v64, v114, v114
	s_waitcnt vmcnt(6)
	v_lshlrev_b32_e32 v118, 16, v44
	v_fmac_f32_e32 v64, v118, v118
	v_and_b32_e32 v119, 0xffff0000, v44
	v_fmac_f32_e32 v64, v119, v119
	v_lshlrev_b32_e32 v120, 16, v45
	v_fmac_f32_e32 v64, v120, v120
	v_and_b32_e32 v121, 0xffff0000, v45
	v_fmac_f32_e32 v64, v121, v121
	v_lshlrev_b32_e32 v134, 16, v46
	v_fmac_f32_e32 v64, v134, v134
	v_and_b32_e32 v135, 0xffff0000, v46
	v_fmac_f32_e32 v64, v135, v135
	v_lshlrev_b32_e32 v136, 16, v47
	v_fmac_f32_e32 v64, v136, v136
	v_and_b32_e32 v137, 0xffff0000, v47
	v_fmac_f32_e32 v64, v137, v137
	s_waitcnt vmcnt(5)
	v_lshlrev_b32_e32 v122, 16, v48
	v_fmac_f32_e32 v64, v122, v122
	v_and_b32_e32 v123, 0xffff0000, v48
	v_fmac_f32_e32 v64, v123, v123
	v_lshlrev_b32_e32 v124, 16, v49
	global_load_dwordx4 v[22:25], v130, s[82:83] offset:16
	global_load_dwordx4 v[26:29], v130, s[82:83]
	v_fmac_f32_e32 v64, v124, v124
	v_and_b32_e32 v49, 0xffff0000, v49
	v_fmac_f32_e32 v64, v49, v49
	v_lshlrev_b32_e32 v125, 16, v50
	v_fmac_f32_e32 v64, v125, v125
	v_and_b32_e32 v131, 0xffff0000, v50
	v_fmac_f32_e32 v64, v131, v131
	v_lshlrev_b32_e32 v132, 16, v51
	v_fmac_f32_e32 v64, v132, v132
	v_and_b32_e32 v133, 0xffff0000, v51
	v_fmac_f32_e32 v64, v133, v133
	s_waitcnt vmcnt(6)
	v_lshlrev_b32_e32 v47, 16, v66
	v_fmac_f32_e32 v64, v47, v47
	v_and_b32_e32 v57, 0xffff0000, v66
	v_fmac_f32_e32 v64, v57, v57
	v_lshlrev_b32_e32 v77, 16, v67
	v_fmac_f32_e32 v64, v77, v77
	v_and_b32_e32 v97, 0xffff0000, v67
	v_fmac_f32_e32 v64, v97, v97
	v_lshlrev_b32_e32 v126, 16, v68
	v_fmac_f32_e32 v64, v126, v126
	v_and_b32_e32 v127, 0xffff0000, v68
	v_fmac_f32_e32 v64, v127, v127
	v_lshlrev_b32_e32 v128, 16, v69
	v_fmac_f32_e32 v64, v128, v128
	v_and_b32_e32 v129, 0xffff0000, v69
	s_waitcnt vmcnt(3)
	v_lshlrev_b32_e32 v75, 16, v34
	s_waitcnt vmcnt(2)
	v_lshlrev_b32_e32 v74, 16, v30
	v_fmac_f32_e32 v64, v129, v129
	v_lshlrev_b32_e32 v38, 16, v33
	v_and_b32_e32 v40, 0xffff0000, v33
	v_lshlrev_b32_e32 v43, 16, v36
	v_and_b32_e32 v33, 0xffff0000, v36
	v_lshlrev_b32_e32 v36, 16, v31
	v_and_b32_e32 v44, 0xffff0000, v31
	v_pk_mul_f32 v[94:95], v[74:75], v[74:75]
	v_and_b32_e32 v31, 0xffff0000, v34
	v_and_b32_e32 v30, 0xffff0000, v30
	v_lshlrev_b32_e32 v48, 16, v17
	v_and_b32_e32 v46, 0xffff0000, v17
	v_lshlrev_b32_e32 v39, 16, v37
	v_and_b32_e32 v41, 0xffff0000, v37
	v_lshlrev_b32_e32 v37, 16, v35
	v_and_b32_e32 v45, 0xffff0000, v35
	v_add_f32_e32 v17, v94, v64
	v_pk_mul_f32 v[34:35], v[30:31], v[30:31]
	v_pk_mul_f32 v[90:91], v[36:37], v[36:37]
	v_add_f32_e32 v17, v34, v17
	v_lshlrev_b32_e32 v42, 16, v32
	v_pk_mul_f32 v[92:93], v[44:45], v[44:45]
	v_add_f32_e32 v17, v90, v17
	v_pk_mul_f32 v[86:87], v[42:43], v[42:43]
	v_and_b32_e32 v32, 0xffff0000, v32
	v_add_f32_e32 v17, v92, v17
	v_pk_mul_f32 v[88:89], v[32:33], v[32:33]
	v_add_f32_e32 v17, v86, v17
	v_pk_mul_f32 v[82:83], v[38:39], v[38:39]
	v_add_f32_e32 v17, v88, v17
	v_pk_mul_f32 v[84:85], v[40:41], v[40:41]
	v_add_f32_e32 v17, v82, v17
	v_lshlrev_b32_e32 v71, 16, v18
	v_lshlrev_b32_e32 v70, 16, v14
	v_add_f32_e32 v17, v84, v17
	v_pk_mul_f32 v[168:169], v[70:71], v[70:71]
	v_and_b32_e32 v73, 0xffff0000, v18
	v_and_b32_e32 v72, 0xffff0000, v14
	v_lshlrev_b32_e32 v62, 16, v16
	v_and_b32_e32 v64, 0xffff0000, v16
	v_lshlrev_b32_e32 v67, 16, v19
	v_lshlrev_b32_e32 v66, 16, v15
	v_and_b32_e32 v68, 0xffff0000, v15
	v_add_f32_e32 v16, v168, v17
	v_pk_mul_f32 v[14:15], v[72:73], v[72:73]
	v_pk_mul_f32 v[162:163], v[66:67], v[66:67]
	v_and_b32_e32 v69, 0xffff0000, v19
	v_add_f32_e32 v14, v14, v16
	v_lshlrev_b32_e32 v63, 16, v20
	v_pk_mul_f32 v[164:165], v[68:69], v[68:69]
	v_add_f32_e32 v14, v162, v14
	v_pk_mul_f32 v[160:161], v[62:63], v[62:63]
	v_and_b32_e32 v65, 0xffff0000, v20
	v_add_f32_e32 v14, v164, v14
	v_and_b32_e32 v51, 0xffff0000, v21
	v_lshlrev_b32_e32 v50, 16, v21
	v_pk_mul_f32 v[20:21], v[64:65], v[64:65]
	v_add_f32_e32 v14, v160, v14
	v_add_f32_e32 v14, v20, v14
	v_fmac_f32_e32 v14, v48, v48
	v_fmac_f32_e32 v14, v46, v46
	v_add_f32_e32 v14, v95, v14
	v_add_f32_e32 v14, v35, v14
	v_add_f32_e32 v14, v91, v14
	v_add_f32_e32 v14, v93, v14
	v_add_f32_e32 v14, v87, v14
	v_add_f32_e32 v14, v89, v14
	v_add_f32_e32 v14, v83, v14
	v_add_f32_e32 v14, v85, v14
	v_add_f32_e32 v14, v169, v14
	v_add_f32_e32 v14, v15, v14
	v_add_f32_e32 v14, v163, v14
	v_add_f32_e32 v14, v165, v14
	v_add_f32_e32 v14, v161, v14
	v_pk_mul_f32 v[80:81], v[50:51], v[50:51]
	v_add_f32_e32 v14, v21, v14
	v_add_f32_e32 v14, v80, v14
	v_add_f32_e32 v14, v81, v14
	v_mov_b32_e32 v15, v14
	s_nop 1
	v_permlane32_swap_b32_e32 v14, v15
	v_add_f32_e32 v14, v14, v15
	v_fmamk_f32 v14, v14, 0x3baaaaab, v186
	v_mul_f32_e32 v15, 0x4f800000, v14
	v_cmp_gt_f32_e32 vcc, s1, v14
	v_add_u32_e32 v34, s0, v98
	v_lshlrev_b32_e32 v84, 1, v56
	v_cndmask_b32_e32 v35, v14, v15, vcc
	v_sqrt_f32_e32 v80, v35
	global_load_dwordx4 v[14:17], v[60:61], off
	global_load_dwordx4 v[18:21], v[78:79], off
	v_lshrrev_b32_e32 v85, 1, v56
	v_and_b32_e32 v86, 3, v56
	v_add_u32_e32 v60, -1, v80
	v_fma_f32 v61, -v60, v80, v35
	v_cmp_ge_f32_e64 s[0:1], 0, v61
	v_add_u32_e32 v61, 1, v80
	v_fma_f32 v78, -v61, v80, v35
	v_cndmask_b32_e64 v60, v80, v60, s[0:1]
	v_cmp_lt_f32_e64 s[0:1], 0, v78
	v_lshlrev_b32_e32 v88, 4, v96
	v_and_or_b32 v86, v85, 4, v86
	v_cndmask_b32_e64 v60, v60, v61, s[0:1]
	v_mul_f32_e32 v61, 0x37800000, v60
	v_cndmask_b32_e32 v60, v60, v61, vcc
	v_cmp_class_f32_e32 vcc, v35, v187
	v_and_b32_e32 v85, 0xfffff0, v76
	v_lshlrev_b32_e32 v87, 1, v76
	v_cndmask_b32_e32 v60, v60, v35, vcc
	v_div_scale_f32 v61, s[0:1], v60, v60, 1.0
	v_rcp_f32_e32 v78, v61
	v_ashrrev_i32_e32 v35, 31, v34
	v_lshl_add_u64 v[34:35], v[34:35], 2, s[6:7]
	global_load_dword v34, v[34:35], off
	v_fma_f32 v35, -v61, v78, 1.0
	v_fmac_f32_e32 v78, v35, v78
	v_div_scale_f32 v35, vcc, 1.0, v60, 1.0
	v_mul_f32_e32 v79, v35, v78
	v_fma_f32 v80, -v61, v79, v35
	v_fmac_f32_e32 v79, v80, v78
	v_fma_f32 v35, -v61, v79, v35
	v_div_fmas_f32 v35, v35, v78, v79
	v_div_fixup_f32 v60, v35, v60, 1.0
	v_mul_f32_e32 v35, v60, v159
	s_waitcnt vmcnt(3)
	v_mul_f32_e32 v26, v26, v35
	v_mul_f32_e32 v35, v60, v158
	v_mul_f32_e32 v27, v27, v35
	v_cvt_pk_bf16_f32 v98, v26, v27
	v_mul_f32_e32 v26, v60, v157
	v_mul_f32_e32 v26, v28, v26
	v_mul_f32_e32 v27, v60, v99
	v_mul_f32_e32 v27, v29, v27
	v_cvt_pk_bf16_f32 v99, v26, v27
	v_mul_f32_e32 v26, v60, v156
	v_mul_f32_e32 v22, v22, v26
	v_mul_f32_e32 v26, v60, v100
	v_mul_f32_e32 v23, v23, v26
	v_cvt_pk_bf16_f32 v100, v22, v23
	v_mul_f32_e32 v22, v60, v155
	v_mul_f32_e32 v23, v60, v101
	v_mul_f32_e32 v22, v24, v22
	v_mul_f32_e32 v23, v25, v23
	v_cvt_pk_bf16_f32 v101, v22, v23
	global_load_dwordx4 v[22:25], v130, s[82:83] offset:64
	global_load_dwordx4 v[26:29], v130, s[82:83] offset:80
	global_load_dwordx4 v[172:175], v130, s[82:83] offset:128
	global_load_dwordx4 v[176:179], v130, s[82:83] offset:144
	global_load_dwordx4 v[198:201], v130, s[82:83] offset:192
	global_load_dwordx4 v[206:209], v130, s[82:83] offset:208
	global_load_dwordx4 v[210:213], v130, s[82:83] offset:256
	global_load_dwordx4 v[214:217], v130, s[82:83] offset:272
	global_load_dwordx4 v[218:221], v130, s[82:83] offset:320
	global_load_dwordx4 v[222:225], v130, s[82:83] offset:336
	global_load_dwordx4 v[226:229], v130, s[82:83] offset:400
	global_load_dwordx4 v[230:233], v130, s[82:83] offset:384
	global_load_dwordx4 v[234:237], v130, s[82:83] offset:464
	global_load_dwordx4 v[238:241], v130, s[82:83] offset:448
	v_mul_f32_e32 v35, v60, v154
	v_mul_f32_e32 v61, v60, v149
	v_mul_f32_e32 v78, v60, v148
	v_mul_f32_e32 v79, v60, v147
	v_mul_f32_e32 v80, v60, v109
	v_mul_f32_e32 v81, v60, v108
	v_mul_f32_e32 v82, v60, v107
	v_mul_f32_e32 v83, v60, v106
	v_mul_f32_e32 v118, v60, v118
	v_mul_f32_e32 v119, v60, v119
	v_mul_f32_e32 v120, v60, v120
	v_mul_f32_e32 v121, v60, v121
	v_mul_f32_e32 v134, v60, v134
	v_mul_f32_e32 v135, v60, v135
	v_mul_f32_e32 v136, v60, v136
	v_mul_f32_e32 v137, v60, v137
	v_mul_f32_e32 v49, v60, v49
	v_and_b32_e32 v76, 0xf0, v88
	v_and_or_b32 v85, v87, 8, v85
	v_lshrrev_b32_e32 v85, 1, v85
	v_mul_f32_e32 v47, v60, v47
	v_mul_f32_e32 v57, v60, v57
	v_mul_f32_e32 v77, v60, v77
	s_lshl_b32 s0, s73, 12
	s_add_i32 s0, s0, 0
	s_add_i32 s0, s0, 0x18800
	s_waitcnt vmcnt(14)
	v_cvt_f32_i32_e32 v170, v34
	s_waitcnt vmcnt(13)
	v_mul_f32_e32 v22, v35, v22
	v_mul_f32_e32 v35, v60, v102
	v_mul_f32_e32 v23, v35, v23
	v_cvt_pk_bf16_f32 v102, v22, v23
	v_mul_f32_e32 v22, v60, v153
	v_mul_f32_e32 v23, v60, v103
	v_mul_f32_e32 v22, v22, v24
	v_mul_f32_e32 v23, v23, v25
	v_cvt_pk_bf16_f32 v103, v22, v23
	v_mul_f32_e32 v22, v60, v152
	v_mul_f32_e32 v23, v60, v104
	s_waitcnt vmcnt(12)
	v_mul_f32_e32 v22, v22, v26
	v_mul_f32_e32 v23, v23, v27
	v_cvt_pk_bf16_f32 v104, v22, v23
	v_mul_f32_e32 v22, v60, v151
	v_mul_f32_e32 v23, v60, v105
	v_mul_f32_e32 v22, v22, v28
	v_mul_f32_e32 v23, v23, v29
	v_cvt_pk_bf16_f32 v105, v22, v23
	v_mul_f32_e32 v35, v60, v150
	s_waitcnt vmcnt(11)
	v_mul_f32_e32 v22, v35, v172
	v_mul_f32_e32 v23, v61, v173
	v_mul_f32_e32 v24, v78, v174
	v_mul_f32_e32 v25, v79, v175
	s_waitcnt vmcnt(10)
	v_mul_f32_e32 v26, v80, v176
	v_mul_f32_e32 v27, v81, v177
	v_mul_f32_e32 v28, v82, v178
	v_mul_f32_e32 v29, v83, v179
	v_cvt_pk_bf16_f32 v106, v22, v23
	v_cvt_pk_bf16_f32 v107, v24, v25
	v_cvt_pk_bf16_f32 v108, v26, v27
	v_cvt_pk_bf16_f32 v109, v28, v29
	v_mul_f32_e32 v35, v60, v145
	v_mul_f32_e32 v61, v60, v143
	v_mul_f32_e32 v78, v60, v112
	v_mul_f32_e32 v79, v60, v111
	v_mul_f32_e32 v80, v60, v110
	v_mul_f32_e32 v81, v60, v146
	v_mul_f32_e32 v82, v60, v144
	v_mul_f32_e32 v83, v60, v113
	s_waitcnt vmcnt(9)
	v_mul_f32_e32 v22, v35, v198
	v_mul_f32_e32 v23, v61, v199
	v_mul_f32_e32 v24, v78, v200
	v_mul_f32_e32 v25, v79, v201
	s_waitcnt vmcnt(8)
	v_mul_f32_e32 v26, v80, v206
	v_mul_f32_e32 v27, v81, v207
	v_mul_f32_e32 v28, v82, v208
	v_mul_f32_e32 v29, v83, v209
	v_cvt_pk_bf16_f32 v110, v22, v23
	v_cvt_pk_bf16_f32 v111, v24, v25
	v_cvt_pk_bf16_f32 v112, v26, v27
	v_cvt_pk_bf16_f32 v113, v28, v29
	v_mul_f32_e32 v35, v60, v142
	v_mul_f32_e32 v61, v60, v141
	v_mul_f32_e32 v78, v60, v140
	v_mul_f32_e32 v79, v60, v139
	v_mul_f32_e32 v80, v60, v117
	v_mul_f32_e32 v81, v60, v116
	v_mul_f32_e32 v82, v60, v115
	v_mul_f32_e32 v83, v60, v114
	s_waitcnt vmcnt(7)
	v_mul_f32_e32 v22, v35, v210
	v_mul_f32_e32 v23, v61, v211
	v_mul_f32_e32 v24, v78, v212
	v_mul_f32_e32 v25, v79, v213
	s_waitcnt vmcnt(6)
	v_mul_f32_e32 v26, v80, v214
	v_mul_f32_e32 v27, v81, v215
	v_mul_f32_e32 v28, v82, v216
	v_mul_f32_e32 v29, v83, v217
	v_cvt_pk_bf16_f32 v114, v22, v23
	v_cvt_pk_bf16_f32 v115, v24, v25
	v_cvt_pk_bf16_f32 v116, v26, v27
	v_cvt_pk_bf16_f32 v117, v28, v29
	v_and_b32_e32 v82, 0xfffff0, v56
	v_lshlrev_b32_e32 v81, 3, v193
	v_and_b32_e32 v80, 0xf0, v195
	v_lshlrev_b32_e32 v83, 8, v56
	v_and_or_b32 v82, v84, 8, v82
	v_cvt_f32_ubyte0_e32 v84, v81
	v_bitop3_b32 v80, v0, v83, v80 bitop3:0xde
	v_mul_f32_e32 v83, 0xbed49a78, v84
	v_cmp_gt_f32_e32 vcc, s2, v83
	v_bfe_u32 v35, v138, 5, 2
	v_or_b32_e32 v88, 1, v81
	v_or_b32_e32 v89, 2, v81
	v_or_b32_e32 v90, 3, v81
	v_or_b32_e32 v91, 4, v81
	v_or_b32_e32 v92, 5, v81
	v_or_b32_e32 v93, 6, v81
	v_or_b32_e32 v94, 7, v81
	v_or_b32_e32 v95, 16, v81
	v_or_b32_e32 v138, 17, v81
	v_or_b32_e32 v139, 18, v81
	v_or_b32_e32 v140, 19, v81
	v_or_b32_e32 v141, 20, v81
	v_or_b32_e32 v142, 21, v81
	v_or_b32_e32 v143, 22, v81
	v_or_b32_e32 v144, 23, v81
	v_lshrrev_b32_e32 v145, 1, v82
	v_lshlrev_b32_e32 v81, 6, v86
	v_cvt_f32_ubyte0_e32 v86, v88
	v_cvt_f32_ubyte0_e32 v87, v89
	v_cvt_f32_ubyte0_e32 v88, v90
	v_cvt_f32_ubyte0_e32 v89, v91
	v_cvt_f32_ubyte0_e32 v90, v92
	v_cvt_f32_ubyte0_e32 v91, v93
	v_cvt_f32_ubyte0_e32 v92, v94
	v_cvt_f32_ubyte0_e32 v93, v95
	v_cvt_f32_ubyte0_e32 v94, v138
	v_cvt_f32_ubyte0_e32 v95, v139
	v_cvt_f32_ubyte0_e32 v138, v140
	v_cvt_f32_ubyte0_e32 v139, v141
	v_cvt_f32_ubyte0_e32 v140, v142
	v_mul_f32_e32 v141, 0xbed49a78, v86
	v_mul_f32_e32 v142, 0xbed49a78, v87
	v_mul_f32_e32 v146, 0xbed49a78, v91
	v_mul_f32_e32 v148, 0xbed49a78, v93
	v_mul_f32_e32 v149, 0xbed49a78, v94
	v_mul_f32_e32 v150, 0xbed49a78, v95
	v_mul_f32_e32 v151, 0xbed49a78, v138
	v_mul_f32_e32 v147, 0xbed49a78, v92
	v_mul_f32_e32 v152, 0xbed49a78, v139
	v_mul_f32_e32 v153, 0xbed49a78, v140
	v_cmp_gt_f32_e64 s[20:21], s2, v141
	v_cmp_gt_f32_e64 s[22:23], s2, v142
	v_cmp_gt_f32_e64 s[30:31], s2, v146
	v_cmp_gt_f32_e64 s[6:7], s2, v148
	v_cmp_gt_f32_e64 s[8:9], s2, v149
	v_cmp_gt_f32_e64 s[10:11], s2, v150
	v_cmp_gt_f32_e64 s[12:13], s2, v151
	v_cndmask_b32_e64 v141, 0, v182, s[22:23]
	v_cmp_gt_f32_e64 s[4:5], s2, v147
	v_cndmask_b32_e64 v147, 0, v182, s[6:7]
	v_cndmask_b32_e64 v148, 0, v182, s[8:9]
	v_cndmask_b32_e64 v149, 0, v182, s[10:11]
	v_cndmask_b32_e64 v150, 0, v182, s[12:13]
	v_cmp_gt_f32_e64 s[14:15], s2, v152
	v_cmp_gt_f32_e64 s[16:17], s2, v153
	v_and_b32_e32 v82, 48, v0
	v_cndmask_b32_e64 v146, 0, v182, s[4:5]
	v_cndmask_b32_e64 v151, 0, v182, s[14:15]
	v_cndmask_b32_e64 v152, 0, v182, s[16:17]
	v_fmac_f32_e32 v141, 0xbed49a78, v87
	v_fmac_f32_e32 v147, 0xbed49a78, v93
	v_fmac_f32_e32 v148, 0xbed49a78, v94
	v_fmac_f32_e32 v149, 0xbed49a78, v95
	v_fmac_f32_e32 v150, 0xbed49a78, v138
	v_fmac_f32_e32 v146, 0xbed49a78, v92
	v_fmac_f32_e32 v151, 0xbed49a78, v139
	v_fmac_f32_e32 v152, 0xbed49a78, v140
	v_cndmask_b32_e64 v87, 0, v183, s[22:23]
	s_waitcnt vmcnt(5)
	v_mul_f32_e32 v26, v118, v218
	v_mul_f32_e32 v27, v119, v219
	v_mul_f32_e32 v28, v120, v220
	v_mul_f32_e32 v29, v121, v221
	s_waitcnt vmcnt(4)
	v_mul_f32_e32 v22, v134, v222
	v_mul_f32_e32 v23, v135, v223
	v_mul_f32_e32 v24, v136, v224
	v_mul_f32_e32 v25, v137, v225
	v_cvt_pk_bf16_f32 v118, v26, v27
	v_cvt_pk_bf16_f32 v119, v28, v29
	v_cvt_pk_bf16_f32 v120, v22, v23
	v_cvt_pk_bf16_f32 v121, v24, v25
	v_cndmask_b32_e32 v137, 0, v182, vcc
	v_fmac_f32_e32 v137, 0xbed49a78, v84
	v_mul_f32_e32 v84, v60, v122
	v_mul_f32_e32 v122, v60, v123
	v_mul_f32_e32 v123, v60, v124
	v_mul_f32_e32 v124, v60, v125
	v_mul_f32_e32 v125, v60, v131
	v_mul_f32_e32 v131, v60, v132
	v_mul_f32_e32 v132, v60, v133
	v_cvt_f32_ubyte0_e32 v134, v143
	v_cvt_f32_ubyte0_e32 v135, v144
	v_or_b32_e32 v136, v145, v35
	v_mul_f32_e32 v143, 0xbed49a78, v88
	v_mul_f32_e32 v144, 0xbed49a78, v89
	v_mul_f32_e32 v145, 0xbed49a78, v90
	v_mul_f32_e32 v155, 0xbed49a78, v135
	v_cmp_gt_f32_e64 s[24:25], s2, v143
	v_cmp_gt_f32_e64 s[26:27], s2, v144
	v_cmp_gt_f32_e64 s[28:29], s2, v145
	v_mul_f32_e32 v154, 0xbed49a78, v134
	v_lshlrev_b32_e32 v83, 9, v136
	v_or_b32_e32 v35, v85, v35
	v_cndmask_b32_e32 v85, 0, v183, vcc
	v_cndmask_b32_e64 v136, 0, v182, s[20:21]
	v_cndmask_b32_e64 v142, 0, v182, s[24:25]
	v_cndmask_b32_e64 v143, 0, v182, s[26:27]
	v_cndmask_b32_e64 v144, 0, v182, s[28:29]
	v_cndmask_b32_e64 v145, 0, v182, s[30:31]
	v_cmp_gt_f32_e32 vcc, s2, v155
	v_cmp_gt_f32_e64 s[18:19], s2, v154
	v_lshlrev_b32_e32 v35, 9, v35
	v_cndmask_b32_e32 v154, 0, v182, vcc
	v_fmac_f32_e32 v136, 0xbed49a78, v86
	v_fmac_f32_e32 v142, 0xbed49a78, v88
	v_fmac_f32_e32 v143, 0xbed49a78, v89
	v_fmac_f32_e32 v144, 0xbed49a78, v90
	v_fmac_f32_e32 v145, 0xbed49a78, v91
	v_exp_f32_e32 v137, v137
	v_fmac_f32_e32 v154, 0xbed49a78, v135
	v_exp_f32_e32 v135, v141
	v_exp_f32_e32 v138, v143
	v_exp_f32_e32 v139, v144
	v_exp_f32_e32 v140, v145
	v_exp_f32_e32 v143, v148
	v_exp_f32_e32 v144, v149
	v_exp_f32_e32 v145, v150
	v_cndmask_b32_e64 v153, 0, v182, s[18:19]
	v_exp_f32_e32 v141, v146
	v_fmac_f32_e32 v153, 0xbed49a78, v134
	v_cndmask_b32_e64 v86, 0, v183, s[20:21]
	v_cndmask_b32_e64 v88, 0, v183, s[24:25]
	v_cndmask_b32_e64 v92, 0, v183, s[6:7]
	v_cndmask_b32_e64 v93, 0, v183, s[8:9]
	v_cndmask_b32_e64 v94, 0, v183, s[10:11]
	v_cndmask_b32_e64 v95, 0, v183, s[12:13]
	v_exp_f32_e32 v148, v153
	v_exp_f32_e32 v149, v154
	v_cndmask_b32_e64 v89, 0, v183, s[26:27]
	v_cndmask_b32_e64 v90, 0, v183, s[28:29]
	v_cndmask_b32_e64 v91, 0, v183, s[30:31]
	v_ldexp_f32 v85, v137, v85
	v_ldexp_f32 v93, v143, v93
	v_ldexp_f32 v94, v144, v94
	v_ldexp_f32 v95, v145, v95
	v_cndmask_b32_e64 v133, 0, v183, s[18:19]
	v_cndmask_b32_e32 v134, 0, v183, vcc
	v_ldexp_f32 v34, v148, v133
	v_ldexp_f32 v171, v149, v134
	v_exp_f32_e32 v146, v151
	v_and_b32_e32 v61, 63, v195
	v_pk_mul_f32 v[74:75], v[60:61], v[74:75] op_sel_hi:[0,1]
	v_pk_mul_f32 v[30:31], v[60:61], v[30:31] op_sel_hi:[0,1]
	v_pk_mul_f32 v[36:37], v[60:61], v[36:37] op_sel_hi:[0,1]
	v_pk_mul_f32 v[44:45], v[60:61], v[44:45] op_sel_hi:[0,1]
	v_pk_mul_f32 v[42:43], v[60:61], v[42:43] op_sel_hi:[0,1]
	v_pk_mul_f32 v[32:33], v[60:61], v[32:33] op_sel_hi:[0,1]
	v_pk_mul_f32 v[38:39], v[60:61], v[38:39] op_sel_hi:[0,1]
	v_pk_mul_f32 v[40:41], v[60:61], v[40:41] op_sel_hi:[0,1]
	s_waitcnt vmcnt(3)
	v_mul_f32_e32 v22, v124, v226
	s_waitcnt vmcnt(2)
	v_mul_f32_e32 v26, v84, v230
	v_mul_f32_e32 v27, v122, v231
	v_mul_f32_e32 v28, v123, v232
	v_mul_f32_e32 v29, v49, v233
	v_mul_f32_e32 v23, v125, v227
	v_mul_f32_e32 v24, v131, v228
	v_mul_f32_e32 v25, v132, v229
	v_cvt_pk_bf16_f32 v122, v26, v27
	v_cvt_pk_bf16_f32 v123, v28, v29
	v_cvt_pk_bf16_f32 v124, v22, v23
	v_cvt_pk_bf16_f32 v125, v24, v25
	v_or3_b32 v84, v35, v81, v82
	v_exp_f32_e32 v35, v136
	v_exp_f32_e32 v136, v142
	v_exp_f32_e32 v142, v147
	v_exp_f32_e32 v147, v152
	v_cndmask_b32_e64 v49, 0, v183, s[4:5]
	v_ldexp_f32 v35, v35, v86
	v_ldexp_f32 v86, v135, v87
	v_ldexp_f32 v87, v136, v88
	v_ldexp_f32 v92, v142, v92
	v_cndmask_b32_e64 v132, 0, v183, s[16:17]
	v_ldexp_f32 v88, v138, v89
	v_ldexp_f32 v89, v139, v90
	v_ldexp_f32 v90, v140, v91
	v_ldexp_f32 v91, v141, v49
	v_mov_b32_e32 v49, v50
	v_mul_f32_e32 v136, v85, v170
	v_mul_f32_e32 v137, v86, v170
	v_mul_f32_e32 v138, v87, v170
	v_mul_f32_e32 v50, v92, v170
	v_mul_f32_e32 v85, v93, v170
	v_mul_f32_e32 v86, v94, v170
	v_mul_f32_e32 v87, v95, v170
	v_mul_f32_e32 v92, v60, v97
	v_mul_f32_e32 v93, v60, v126
	v_mul_f32_e32 v94, v60, v127
	v_mul_f32_e32 v95, v60, v128
	v_mul_f32_e32 v97, v60, v129
	v_ldexp_f32 v132, v147, v132
	v_mul_f32_e32 v140, v89, v170
	v_mul_f32_e32 v89, v132, v170
	v_cndmask_b32_e64 v131, 0, v183, s[14:15]
	v_ldexp_f32 v131, v146, v131
	v_mul_f32_e32 v35, v35, v170
	v_mul_f32_e32 v139, v88, v170
	v_mul_f32_e32 v141, v90, v170
	v_mul_f32_e32 v91, v91, v170
	v_mul_f32_e32 v88, v131, v170
	v_mul_f32_e32 v90, v34, v170
	v_mul_f32_e32 v34, 0.15915494, v136
	v_mul_f32_e32 v131, 0.15915494, v35
	v_mul_f32_e32 v142, 0.15915494, v141
	v_mul_f32_e32 v143, 0.15915494, v91
	v_rndne_f32_e32 v34, v34
	v_rndne_f32_e32 v131, v131
	v_rndne_f32_e32 v142, v142
	v_rndne_f32_e32 v143, v143
	v_fmac_f32_e32 v136, 0xc0c90fdb, v34
	v_fmac_f32_e32 v35, 0xc0c90fdb, v131
	v_fmac_f32_e32 v141, 0xc0c90fdb, v142
	v_fmac_f32_e32 v91, 0xc0c90fdb, v143
	v_fmac_f32_e32 v136, 0x343bbd2e, v34
	v_fmac_f32_e32 v35, 0x343bbd2e, v131
	v_fmac_f32_e32 v141, 0x343bbd2e, v142
	v_fmac_f32_e32 v91, 0x343bbd2e, v143
	v_mul_f32_e32 v147, 0.15915494, v141
	v_mul_f32_e32 v91, 0.15915494, v91
	v_sin_f32_e32 v146, v147
	v_cos_f32_e32 v147, v147
	v_sin_f32_e32 v149, v91
	v_cos_f32_e32 v148, v91
	v_mov_b32_e32 v163, v146
	v_mov_b32_e32 v162, v147
	v_mov_b32_e32 v164, v149
	v_mov_b32_e32 v165, v148
	v_lshlrev_b32_e32 v79, 4, v61
	v_add_u32_e32 v196, s0, v79
	v_mul_f32_e32 v91, 0.15915494, v88
	v_rndne_f32_e32 v91, v91
	v_pk_mul_f32 v[70:71], v[60:61], v[70:71] op_sel_hi:[0,1]
	v_pk_mul_f32 v[72:73], v[60:61], v[72:73] op_sel_hi:[0,1]
	v_pk_mul_f32 v[48:49], v[60:61], v[48:49] op_sel_hi:[0,1]
	v_fmac_f32_e32 v88, 0xc0c90fdb, v91
	v_pk_mul_f32 v[66:67], v[60:61], v[66:67] op_sel_hi:[0,1]
	v_fmac_f32_e32 v88, 0x343bbd2e, v91
	v_pk_mul_f32 v[64:65], v[60:61], v[64:65] op_sel_hi:[0,1]
	v_pk_mul_f32 v[68:69], v[60:61], v[68:69] op_sel_hi:[0,1]
	v_pk_mul_f32 v[62:63], v[60:61], v[62:63] op_sel_hi:[0,1]
	s_waitcnt vmcnt(1)
	v_mul_f32_e32 v22, v93, v234
	s_waitcnt vmcnt(0)
	v_mul_f32_e32 v26, v47, v238
	v_mul_f32_e32 v27, v57, v239
	v_mul_f32_e32 v28, v77, v240
	v_mul_f32_e32 v29, v92, v241
	v_mul_f32_e32 v23, v94, v235
	v_mul_f32_e32 v24, v95, v236
	v_mul_f32_e32 v25, v97, v237
	v_cvt_pk_bf16_f32 v126, v26, v27
	v_cvt_pk_bf16_f32 v127, v28, v29
	v_cvt_pk_bf16_f32 v128, v22, v23
	v_cvt_pk_bf16_f32 v129, v24, v25
	global_load_dwordx4 v[22:25], v130, s[82:83] offset:528
	global_load_dwordx4 v[26:29], v130, s[82:83] offset:512
	global_load_dwordx4 v[92:95], v130, s[82:83] offset:656
	global_load_dwordx4 v[132:135], v130, s[82:83] offset:640
	v_mul_f32_e32 v47, 0.15915494, v137
	v_mul_f32_e32 v57, 0.15915494, v138
	v_mul_f32_e32 v77, 0.15915494, v139
	v_mul_f32_e32 v97, 0.15915494, v140
	v_rndne_f32_e32 v47, v47
	v_rndne_f32_e32 v57, v57
	v_rndne_f32_e32 v77, v77
	v_rndne_f32_e32 v97, v97
	v_fmac_f32_e32 v137, 0xc0c90fdb, v47
	v_fmac_f32_e32 v138, 0xc0c90fdb, v57
	v_fmac_f32_e32 v139, 0xc0c90fdb, v77
	v_fmac_f32_e32 v140, 0xc0c90fdb, v97
	v_fmac_f32_e32 v137, 0x343bbd2e, v47
	v_fmac_f32_e32 v138, 0x343bbd2e, v57
	v_fmac_f32_e32 v139, 0x343bbd2e, v77
	v_fmac_f32_e32 v140, 0x343bbd2e, v97
	v_mul_f32_e32 v47, 0.15915494, v136
	v_mul_f32_e32 v57, 0.15915494, v35
	v_mul_f32_e32 v77, 0.15915494, v137
	v_mul_f32_e32 v97, 0.15915494, v138
	v_mul_f32_e32 v131, 0.15915494, v139
	v_mul_f32_e32 v144, 0.15915494, v140
	v_sin_f32_e32 v34, v47
	v_cos_f32_e32 v35, v47
	v_sin_f32_e32 v137, v57
	v_cos_f32_e32 v136, v57
	v_sin_f32_e32 v138, v77
	v_cos_f32_e32 v139, v77
	v_sin_f32_e32 v141, v97
	v_cos_f32_e32 v140, v97
	v_sin_f32_e32 v142, v131
	v_cos_f32_e32 v143, v131
	v_sin_f32_e32 v145, v144
	v_cos_f32_e32 v144, v144
	v_mov_b32_e32 v150, v35
	v_mov_b32_e32 v151, v34
	v_mov_b32_e32 v152, v137
	v_mov_b32_e32 v153, v136
	v_mov_b32_e32 v154, v139
	v_mov_b32_e32 v155, v138
	v_mov_b32_e32 v156, v141
	v_mov_b32_e32 v157, v140
	v_mov_b32_e32 v158, v143
	v_mov_b32_e32 v159, v142
	v_mov_b32_e32 v160, v145
	v_mov_b32_e32 v161, v144
	v_mul_f32_e32 v57, 0.15915494, v50
	v_rndne_f32_e32 v57, v57
	v_mul_f32_e32 v47, v171, v170
	v_mul_f32_e32 v77, 0.15915494, v87
	v_fmac_f32_e32 v50, 0xc0c90fdb, v57
	v_rndne_f32_e32 v77, v77
	v_fmac_f32_e32 v50, 0x343bbd2e, v57
	v_fmac_f32_e32 v87, 0xc0c90fdb, v77
	v_mul_f32_e32 v50, 0.15915494, v50
	v_fmac_f32_e32 v87, 0x343bbd2e, v77
	v_lshlrev_b32_e32 v78, 8, v96
	v_add_u32_e32 v203, 0, v84
	v_add_u32_e32 v204, 0, v80
	s_waitcnt vmcnt(2)
	v_mov_b32_e32 v168, v26
	v_mov_b32_e32 v26, v28
	s_waitcnt vmcnt(0)
	v_mov_b32_e32 v169, v132
	v_mov_b32_e32 v132, v27
	v_mov_b32_e32 v27, v134
	v_mov_b32_e32 v134, v29
	v_mov_b32_e32 v28, v22
	v_mov_b32_e32 v29, v92
	v_mov_b32_e32 v92, v23
	v_mov_b32_e32 v22, v24
	v_mov_b32_e32 v23, v94
	v_mov_b32_e32 v94, v25
	v_pk_mul_f32 v[24:25], v[74:75], v[168:169]
	v_pk_mul_f32 v[30:31], v[30:31], v[132:133]
	v_pk_mul_f32 v[26:27], v[36:37], v[26:27]
	v_pk_mul_f32 v[36:37], v[44:45], v[134:135]
	v_pk_mul_f32 v[28:29], v[42:43], v[28:29]
	v_pk_mul_f32 v[32:33], v[32:33], v[92:93]
	v_pk_mul_f32 v[22:23], v[38:39], v[22:23]
	v_pk_mul_f32 v[38:39], v[40:41], v[94:95]
	v_pk_mul_f32 v[40:41], v[150:151], v[24:25]
	v_pk_mul_f32 v[24:25], v[34:35], v[24:25]
	v_pk_mul_f32 v[34:35], v[136:137], v[30:31]
	v_pk_mul_f32 v[30:31], v[152:153], v[30:31]
	v_pk_mul_f32 v[42:43], v[154:155], v[26:27]
	v_pk_mul_f32 v[26:27], v[138:139], v[26:27]
	v_pk_mul_f32 v[44:45], v[140:141], v[36:37]
	v_pk_mul_f32 v[36:37], v[156:157], v[36:37]
	v_pk_mul_f32 v[74:75], v[158:159], v[28:29]
	v_pk_mul_f32 v[28:29], v[142:143], v[28:29]
	v_pk_mul_f32 v[92:93], v[144:145], v[32:33]
	v_pk_mul_f32 v[32:33], v[160:161], v[32:33]
	v_pk_mul_f32 v[94:95], v[162:163], v[22:23]
	v_pk_mul_f32 v[22:23], v[146:147], v[22:23]
	v_pk_mul_f32 v[132:133], v[148:149], v[38:39]
	v_pk_mul_f32 v[38:39], v[164:165], v[38:39]
	v_sub_f32_e32 v40, v40, v41
	v_add_f32_e32 v24, v24, v25
	v_sub_f32_e32 v25, v34, v35
	v_add_f32_e32 v30, v30, v31
	v_sub_f32_e32 v31, v42, v43
	v_add_f32_e32 v26, v26, v27
	v_sub_f32_e32 v27, v44, v45
	v_add_f32_e32 v41, v36, v37
	v_sub_f32_e32 v36, v74, v75
	v_add_f32_e32 v28, v28, v29
	v_sub_f32_e32 v29, v92, v93
	v_add_f32_e32 v32, v32, v33
	v_sub_f32_e32 v33, v94, v95
	v_add_f32_e32 v22, v22, v23
	v_sub_f32_e32 v23, v132, v133
	v_add_f32_e32 v38, v38, v39
	v_cvt_pk_bf16_f32 v34, v40, v25
	v_cvt_pk_bf16_f32 v35, v31, v27
	v_cvt_pk_bf16_f32 v36, v36, v29
	v_cvt_pk_bf16_f32 v37, v33, v23
	v_cvt_pk_bf16_f32 v42, v24, v30
	v_cvt_pk_bf16_f32 v43, v26, v41
	v_cvt_pk_bf16_f32 v44, v28, v32
	v_cvt_pk_bf16_f32 v45, v22, v38
	global_load_dwordx4 v[22:25], v130, s[82:83] offset:592
	global_load_dwordx4 v[38:41], v130, s[82:83] offset:576
	global_load_dwordx4 v[26:29], v130, s[82:83] offset:720
	global_load_dwordx4 v[30:33], v130, s[82:83] offset:704
	v_mul_f32_e32 v93, 0.15915494, v90
	v_mul_f32_e32 v74, 0.15915494, v85
	v_rndne_f32_e32 v93, v93
	v_mul_f32_e32 v75, 0.15915494, v86
	v_mul_f32_e32 v92, 0.15915494, v89
	v_rndne_f32_e32 v74, v74
	v_fmac_f32_e32 v90, 0xc0c90fdb, v93
	v_mul_f32_e32 v94, 0.15915494, v47
	v_rndne_f32_e32 v75, v75
	v_rndne_f32_e32 v92, v92
	v_fmac_f32_e32 v85, 0xc0c90fdb, v74
	v_fmac_f32_e32 v90, 0x343bbd2e, v93
	v_rndne_f32_e32 v94, v94
	v_fmac_f32_e32 v86, 0xc0c90fdb, v75
	v_fmac_f32_e32 v89, 0xc0c90fdb, v92
	v_fmac_f32_e32 v85, 0x343bbd2e, v74
	v_mul_f32_e32 v97, 0.15915494, v90
	v_fmac_f32_e32 v47, 0xc0c90fdb, v94
	v_fmac_f32_e32 v86, 0x343bbd2e, v75
	v_fmac_f32_e32 v89, 0x343bbd2e, v92
	v_mul_f32_e32 v57, 0.15915494, v85
	v_sin_f32_e32 v74, v50
	v_cos_f32_e32 v75, v50
	v_sin_f32_e32 v131, v97
	v_cos_f32_e32 v130, v97
	v_fmac_f32_e32 v47, 0x343bbd2e, v94
	v_mul_f32_e32 v77, 0.15915494, v86
	v_mul_f32_e32 v85, 0.15915494, v87
	v_mul_f32_e32 v94, 0.15915494, v89
	v_sin_f32_e32 v87, v57
	v_cos_f32_e32 v86, v57
	v_sin_f32_e32 v95, v94
	v_cos_f32_e32 v94, v94
	ds_write_b128 v196, v[34:37]
	ds_write_b128 v196, v[42:45] offset:2048
	v_mov_b32_e32 v132, v75
	v_mov_b32_e32 v133, v74
	v_mov_b32_e32 v144, v131
	v_mov_b32_e32 v145, v130
	v_mul_f32_e32 v47, 0.15915494, v47
	v_mul_f32_e32 v93, 0.15915494, v88
	v_mov_b32_e32 v142, v95
	v_mov_b32_e32 v143, v94
	v_sin_f32_e32 v88, v77
	v_cos_f32_e32 v89, v77
	v_sin_f32_e32 v91, v85
	v_cos_f32_e32 v90, v85
	v_sin_f32_e32 v92, v93
	v_cos_f32_e32 v93, v93
	v_mov_b32_e32 v134, v87
	v_mov_b32_e32 v135, v86
	v_mov_b32_e32 v136, v89
	v_mov_b32_e32 v137, v88
	v_mov_b32_e32 v138, v91
	v_mov_b32_e32 v139, v90
	v_mov_b32_e32 v140, v93
	v_mov_b32_e32 v141, v92
	s_waitcnt vmcnt(2)
	v_mov_b32_e32 v34, v38
	v_mov_b32_e32 v38, v22
	s_waitcnt vmcnt(0)
	v_mov_b32_e32 v35, v30
	v_mov_b32_e32 v30, v39
	v_mov_b32_e32 v39, v26
	v_mov_b32_e32 v26, v23
	v_mov_b32_e32 v22, v24
	v_mov_b32_e32 v23, v28
	v_mov_b32_e32 v36, v40
	v_mov_b32_e32 v37, v32
	v_pk_mul_f32 v[34:35], v[70:71], v[34:35]
	v_pk_mul_f32 v[30:31], v[72:73], v[30:31]
	v_pk_mul_f32 v[22:23], v[48:49], v[22:23]
	v_mov_b32_e32 v32, v41
	v_pk_mul_f32 v[36:37], v[66:67], v[36:37]
	v_pk_mul_f32 v[40:41], v[132:133], v[34:35]
	v_pk_mul_f32 v[34:35], v[74:75], v[34:35]
	v_pk_mul_f32 v[42:43], v[86:87], v[30:31]
	v_pk_mul_f32 v[66:67], v[130:131], v[22:23]
	v_pk_mul_f32 v[22:23], v[144:145], v[22:23]
	v_pk_mul_f32 v[26:27], v[64:65], v[26:27]
	v_add_f32_e32 v34, v34, v35
	v_sub_f32_e32 v35, v42, v43
	v_add_f32_e32 v43, v22, v23
	v_sin_f32_e32 v23, v47
	v_cos_f32_e32 v22, v47
	v_pk_mul_f32 v[64:65], v[94:95], v[26:27]
	v_pk_mul_f32 v[26:27], v[142:143], v[26:27]
	v_mov_b32_e32 v47, v51
	v_sub_f32_e32 v40, v40, v41
	v_add_f32_e32 v41, v26, v27
	v_pk_mul_f32 v[26:27], v[60:61], v[46:47] op_sel_hi:[0,1]
	v_mov_b32_e32 v28, v25
	v_pk_mul_f32 v[24:25], v[26:27], v[28:29]
	v_pk_mul_f32 v[32:33], v[68:69], v[32:33]
	v_pk_mul_f32 v[26:27], v[22:23], v[24:25]
	v_pk_mul_f32 v[38:39], v[62:63], v[38:39]
	v_sub_f32_e32 v28, v26, v27
	v_mov_b32_e32 v26, v23
	v_mov_b32_e32 v27, v22
	v_pk_mul_f32 v[30:31], v[134:135], v[30:31]
	v_pk_mul_f32 v[44:45], v[136:137], v[36:37]
	v_pk_mul_f32 v[36:37], v[88:89], v[36:37]
	v_pk_mul_f32 v[48:49], v[90:91], v[32:33]
	v_pk_mul_f32 v[32:33], v[138:139], v[32:33]
	v_pk_mul_f32 v[62:63], v[140:141], v[38:39]
	v_pk_mul_f32 v[38:39], v[92:93], v[38:39]
	v_pk_mul_f32 v[22:23], v[26:27], v[24:25]
	v_add_f32_e32 v30, v30, v31
	v_sub_f32_e32 v31, v44, v45
	v_add_f32_e32 v36, v36, v37
	v_sub_f32_e32 v37, v48, v49
	v_add_f32_e32 v32, v32, v33
	v_sub_f32_e32 v33, v62, v63
	v_add_f32_e32 v38, v38, v39
	v_sub_f32_e32 v39, v64, v65
	v_sub_f32_e32 v42, v66, v67
	v_add_f32_e32 v29, v22, v23
	v_cvt_pk_bf16_f32 v22, v40, v35
	v_cvt_pk_bf16_f32 v23, v31, v37
	v_cvt_pk_bf16_f32 v24, v33, v39
	v_cvt_pk_bf16_f32 v25, v42, v28
	v_cvt_pk_bf16_f32 v26, v34, v30
	v_cvt_pk_bf16_f32 v27, v36, v32
	v_cvt_pk_bf16_f32 v28, v38, v41
	v_cvt_pk_bf16_f32 v29, v43, v29
	ds_write_b128 v196, v[22:25] offset:1024
	ds_write_b128 v196, v[26:29] offset:3072
	v_or3_b32 v22, v83, v81, v82
	v_add_u32_e32 v202, 0, v22
	s_waitcnt vmcnt(0)
	ds_write_b128 v202, v[10:13]
	ds_write_b128 v203, v[6:9]
	v_bitop3_b32 v6, v52, v78, v76 bitop3:0xde
	v_add_u32_e32 v205, 0, v6
	ds_write_b128 v204, v[14:17] offset:32768
	ds_write_b128 v204, v[18:21] offset:40960
	ds_write_b128 v205, v[2:5] offset:49152
	v_add_u32_e32 v2, 64, v56
	v_ashrrev_i32_e32 v3, 31, v2
	v_add_u32_e32 v6, 0x60, v56
	v_lshlrev_b64 v[4:5], 12, v[2:3]
	v_ashrrev_i32_e32 v7, 31, v6
	v_lshl_add_u64 v[4:5], s[80:81], 0, v[4:5]
	v_lshlrev_b64 v[8:9], 12, v[6:7]
	v_lshl_add_u64 v[4:5], v[4:5], 0, v[0:1]
	v_lshl_add_u64 v[8:9], s[80:81], 0, v[8:9]
	s_waitcnt lgkmcnt(0)
	s_barrier
	v_lshl_add_u64 v[8:9], v[8:9], 0, v[0:1]
	global_load_dwordx4 v[34:37], v[4:5], off
	global_load_dwordx4 v[38:41], v[8:9], off
	v_mad_i64_i32 v[2:3], s[0:1], v2, s75, v[166:167]
	v_mad_i64_i32 v[4:5], s[0:1], v6, s75, v[166:167]
	v_lshl_add_u64 v[2:3], v[2:3], 0, v[0:1]
	v_lshl_add_u64 v[4:5], v[4:5], 0, v[0:1]
	v_add_u32_e32 v0, 64, v96
	global_load_dwordx4 v[42:45], v[2:3], off
	global_load_dwordx4 v[46:49], v[4:5], off
	v_mad_i64_i32 v[2:3], s[0:1], v0, s75, v[166:167]
	v_lshl_add_u64 v[2:3], v[2:3], 0, v[52:53]
	global_load_dwordx4 v[50:53], v[2:3], off offset:256
	v_lshlrev_b32_e32 v0, 2, v193
	v_sub_u32_e32 v2, v194, v0
	v_add_u32_e32 v201, s78, v2
	s_movk_i32 s0, 0xf0
	v_lshlrev_b32_e32 v57, 8, v194
	v_bitop3_b32 v60, v58, v59, s0 bitop3:0x78
	v_add3_u32 v207, 0, v60, v57
	ds_read_b128 v[2:5], v207 offset:32768
	ds_read_b128 v[6:9], v207 offset:40960
	v_and_b32_e32 v72, 0xf0, v59
	v_bitop3_b32 v62, v58, v72, 32 bitop3:0x36
	s_waitcnt lgkmcnt(1)
	v_mfma_f32_32x32x16_bf16 v[18:33], v[2:5], v[98:101], 0
	v_add3_u32 v208, 0, v62, v57
	ds_read_b128 v[64:67], v208 offset:32768
	ds_read_b128 v[68:71], v208 offset:40960
	v_bitop3_b32 v63, v58, v72, 64 bitop3:0x36
	v_add3_u32 v209, 0, v63, v57
	s_movk_i32 s0, 0x60
	v_bitop3_b32 v58, v58, v72, s0 bitop3:0x36
	v_add3_u32 v210, 0, v58, v57
	s_waitcnt lgkmcnt(2)
	v_mfma_f32_32x32x16_bf16 v[2:17], v[6:9], v[98:101], 0
	s_cmp_gt_i32 s78, 62
	s_waitcnt lgkmcnt(1)
	v_mfma_f32_32x32x16_bf16 v[18:33], v[64:67], v[102:105], v[18:33]
	s_waitcnt lgkmcnt(0)
	v_mfma_f32_32x32x16_bf16 v[2:17], v[68:71], v[102:105], v[2:17]
	ds_read_b128 v[64:67], v209 offset:32768
	ds_read_b128 v[68:71], v209 offset:40960
	s_waitcnt lgkmcnt(1)
	v_mfma_f32_32x32x16_bf16 v[18:33], v[64:67], v[106:109], v[18:33]
	s_waitcnt lgkmcnt(0)
	v_mfma_f32_32x32x16_bf16 v[2:17], v[68:71], v[106:109], v[2:17]
	ds_read_b128 v[64:67], v210 offset:32768
	ds_read_b128 v[68:71], v210 offset:40960
	s_waitcnt lgkmcnt(1)
	v_mfma_f32_32x32x16_bf16 v[18:33], v[64:67], v[110:113], v[18:33]
	v_and_b32_e32 v64, 8, v195
	v_cmp_eq_u32_e32 vcc, 0, v64
	s_nop 1
	v_cndmask_b32_e32 v206, v188, v189, vcc
	v_mov_b32_e32 v64, v206
	s_waitcnt lgkmcnt(0)
	v_mfma_f32_32x32x16_bf16 v[2:17], v[68:71], v[110:113], v[2:17]
	v_add_u32_e32 v68, v207, v64
	ds_read_b128 v[64:67], v68 offset:32768
	ds_read_b128 v[68:71], v68 offset:40960
	s_waitcnt lgkmcnt(1)
	v_mfma_f32_32x32x16_bf16 v[18:33], v[64:67], v[114:117], v[18:33]
	v_mov_b32_e32 v64, v206
	s_waitcnt lgkmcnt(0)
	v_mfma_f32_32x32x16_bf16 v[2:17], v[68:71], v[114:117], v[2:17]
	v_add_u32_e32 v68, v208, v64
	ds_read_b128 v[64:67], v68 offset:32768
	ds_read_b128 v[68:71], v68 offset:40960
	s_waitcnt lgkmcnt(1)
	v_mfma_f32_32x32x16_bf16 v[18:33], v[64:67], v[118:121], v[18:33]
	v_mov_b32_e32 v64, v206
	s_waitcnt lgkmcnt(0)
	v_mfma_f32_32x32x16_bf16 v[2:17], v[68:71], v[118:121], v[2:17]
	v_add_u32_e32 v68, v209, v64
	ds_read_b128 v[64:67], v68 offset:32768
	ds_read_b128 v[68:71], v68 offset:40960
	s_waitcnt lgkmcnt(1)
	v_mfma_f32_32x32x16_bf16 v[18:33], v[64:67], v[122:125], v[18:33]
	v_mov_b32_e32 v64, v206
	s_waitcnt lgkmcnt(0)
	v_mfma_f32_32x32x16_bf16 v[2:17], v[68:71], v[122:125], v[2:17]
	v_add_u32_e32 v68, v210, v64
	ds_read_b128 v[64:67], v68 offset:32768
	ds_read_b128 v[68:71], v68 offset:40960
	s_waitcnt lgkmcnt(1)
	v_mfma_f32_32x32x16_bf16 v[18:33], v[64:67], v[126:129], v[18:33]
	s_waitcnt lgkmcnt(0)
	v_mfma_f32_32x32x16_bf16 v[2:17], v[68:71], v[126:129], v[2:17]
	ds_read_b128 v[64:67], v207 offset:49152
	ds_read_b128 v[68:71], v196
	ds_read_b128 v[72:75], v207 offset:57344
	ds_read_b128 v[82:85], v196 offset:1024
	s_waitcnt lgkmcnt(2)
	v_mfma_f32_32x32x16_bf16 v[18:33], v[64:67], v[68:71], v[18:33]
	s_waitcnt lgkmcnt(1)
	v_mfma_f32_32x32x16_bf16 v[2:17], v[72:75], v[68:71], v[2:17]
	ds_read_b128 v[64:67], v208 offset:49152
	ds_read_b128 v[68:71], v208 offset:57344
	s_waitcnt lgkmcnt(1)
	v_mfma_f32_32x32x16_bf16 v[18:33], v[64:67], v[82:85], v[18:33]
	s_waitcnt lgkmcnt(0)
	v_mfma_f32_32x32x16_bf16 v[2:17], v[68:71], v[82:85], v[2:17]
	ds_read_b128 v[64:67], v209 offset:49152
	ds_read_b128 v[68:71], v196 offset:2048
	ds_read_b128 v[72:75], v209 offset:57344
	ds_read_b128 v[82:85], v196 offset:3072
	s_waitcnt lgkmcnt(2)
	v_mfma_f32_32x32x16_bf16 v[18:33], v[64:67], v[68:71], v[18:33]
	s_waitcnt lgkmcnt(1)
	v_mfma_f32_32x32x16_bf16 v[2:17], v[72:75], v[68:71], v[2:17]
	ds_read_b128 v[64:67], v210 offset:49152
	ds_read_b128 v[68:71], v210 offset:57344
	s_waitcnt lgkmcnt(1)
	v_mfma_f32_32x32x16_bf16 v[18:33], v[64:67], v[82:85], v[18:33]
	s_waitcnt lgkmcnt(0)
	v_mfma_f32_32x32x16_bf16 v[2:17], v[68:71], v[82:85], v[2:17]
	s_cbranch_scc1 .LBB0_1053
	v_cmp_gt_i32_e64 s[64:65], 26, v201
	v_cmp_gt_i32_e64 s[66:67], 27, v201
	v_cmp_gt_i32_e64 s[62:63], 25, v201
	s_and_b64 s[64:65], s[66:67], s[64:65]
	v_cmp_gt_i32_e64 s[60:61], 24, v201
	s_and_b64 s[62:63], s[64:65], s[62:63]
	v_cmp_gt_i32_e64 s[58:59], 19, v201
	s_and_b64 s[60:61], s[62:63], s[60:61]
	v_cmp_gt_i32_e64 s[56:57], 18, v201
	s_and_b64 s[58:59], s[60:61], s[58:59]
	v_cmp_gt_i32_e64 s[54:55], 17, v201
	s_and_b64 s[56:57], s[58:59], s[56:57]
	v_cmp_gt_i32_e64 s[52:53], 16, v201
	s_and_b64 s[54:55], s[56:57], s[54:55]
	v_cmp_gt_i32_e64 s[50:51], 11, v201
	s_and_b64 s[52:53], s[54:55], s[52:53]
	v_cmp_gt_i32_e64 s[48:49], 10, v201
	s_and_b64 s[50:51], s[52:53], s[50:51]
	v_cmp_gt_i32_e64 s[46:47], 9, v201
	s_and_b64 s[48:49], s[50:51], s[48:49]
	v_cmp_gt_i32_e64 s[44:45], 8, v201
	s_and_b64 s[46:47], s[48:49], s[46:47]
	v_cmp_gt_i32_e64 s[38:39], 3, v201
	s_and_b64 s[44:45], s[46:47], s[44:45]
	v_cmp_gt_i32_e64 s[36:37], 2, v201
	s_and_b64 s[38:39], s[44:45], s[38:39]
	v_cmp_gt_i32_e64 s[34:35], 1, v201
	s_and_b64 s[36:37], s[38:39], s[36:37]
	v_cmp_gt_i32_e64 s[0:1], 0, v201
	s_and_b64 s[34:35], s[36:37], s[34:35]
	s_and_b64 s[0:1], s[34:35], s[0:1]
	v_cmp_gt_i32_e64 s[30:31], 58, v201
	v_cndmask_b32_e64 v18, v18, v190, s[0:1]
	v_cmp_gt_i32_e64 s[0:1], 59, v201
	v_cmp_gt_i32_e64 s[28:29], 57, v201
	v_cmp_gt_i32_e64 s[26:27], 56, v201
	v_cndmask_b32_e64 v17, v17, v190, s[0:1]
	s_and_b64 s[0:1], s[0:1], s[30:31]
	v_cndmask_b32_e64 v16, v16, v190, s[0:1]
	s_and_b64 s[0:1], s[0:1], s[28:29]
	v_cmp_gt_i32_e64 s[24:25], 51, v201
	v_cndmask_b32_e64 v15, v15, v190, s[0:1]
	s_and_b64 s[0:1], s[0:1], s[26:27]
	v_cmp_gt_i32_e64 s[22:23], 50, v201
	v_cndmask_b32_e64 v14, v14, v190, s[0:1]
	s_and_b64 s[0:1], s[0:1], s[24:25]
	v_cmp_gt_i32_e64 s[20:21], 49, v201
	v_cndmask_b32_e64 v13, v13, v190, s[0:1]
	s_and_b64 s[0:1], s[0:1], s[22:23]
	v_cmp_gt_i32_e64 s[18:19], 48, v201
	v_cndmask_b32_e64 v12, v12, v190, s[0:1]
	s_and_b64 s[0:1], s[0:1], s[20:21]
	v_cmp_gt_i32_e64 s[16:17], 43, v201
	v_cndmask_b32_e64 v11, v11, v190, s[0:1]
	s_and_b64 s[0:1], s[0:1], s[18:19]
	v_cmp_gt_i32_e64 s[14:15], 42, v201
	v_cndmask_b32_e64 v10, v10, v190, s[0:1]
	s_and_b64 s[0:1], s[0:1], s[16:17]
	v_cmp_gt_i32_e64 s[12:13], 41, v201
	v_cndmask_b32_e64 v9, v9, v190, s[0:1]
	s_and_b64 s[0:1], s[0:1], s[14:15]
	v_cmp_gt_i32_e64 s[10:11], 40, v201
	v_cndmask_b32_e64 v8, v8, v190, s[0:1]
	s_and_b64 s[0:1], s[0:1], s[12:13]
	v_cmp_gt_i32_e64 s[8:9], 35, v201
	v_cndmask_b32_e64 v7, v7, v190, s[0:1]
	s_and_b64 s[0:1], s[0:1], s[10:11]
	v_cmp_gt_i32_e64 s[6:7], 34, v201
	v_cndmask_b32_e64 v6, v6, v190, s[0:1]
	s_and_b64 s[0:1], s[0:1], s[8:9]
	v_cmp_gt_i32_e64 s[4:5], 33, v201
	v_cndmask_b32_e64 v5, v5, v190, s[0:1]
	s_and_b64 s[0:1], s[0:1], s[6:7]
	v_cmp_gt_i32_e32 vcc, 32, v201
	v_cndmask_b32_e64 v4, v4, v190, s[0:1]
	s_and_b64 s[0:1], s[0:1], s[4:5]
	s_and_b64 vcc, s[0:1], vcc
	v_cndmask_b32_e64 v33, v33, v190, s[66:67]
	v_cndmask_b32_e64 v32, v32, v190, s[64:65]
	v_cndmask_b32_e64 v31, v31, v190, s[62:63]
	v_cndmask_b32_e64 v30, v30, v190, s[60:61]
	v_cndmask_b32_e64 v29, v29, v190, s[58:59]
	v_cndmask_b32_e64 v28, v28, v190, s[56:57]
	v_cndmask_b32_e64 v27, v27, v190, s[54:55]
	v_cndmask_b32_e64 v26, v26, v190, s[52:53]
	v_cndmask_b32_e64 v25, v25, v190, s[50:51]
	v_cndmask_b32_e64 v24, v24, v190, s[48:49]
	v_cndmask_b32_e64 v23, v23, v190, s[46:47]
	v_cndmask_b32_e64 v22, v22, v190, s[44:45]
	v_cndmask_b32_e64 v21, v21, v190, s[38:39]
	v_cndmask_b32_e64 v20, v20, v190, s[36:37]
	v_cndmask_b32_e64 v19, v19, v190, s[34:35]
	v_cndmask_b32_e64 v3, v3, v190, s[0:1]
	v_cndmask_b32_e32 v2, v2, v190, vcc
